# passC0: SSD pass C item prologue issues its 12 staging loads (dt/cumsum, C/B tiles) up front with counted waits instead of load-wait-store per trip
# speedup vs baseline: 1.0068x; 1.0003x over previous
.LBB0_646:
	s_mov_b64 s[76:77], s[96:97]
	s_ashr_i32 s97, s33, 6
	s_bfe_u32 s96, s33, 0x50001
	s_lshl_b32 s86, s97, 12
	s_lshl_b32 s87, s96, 7
	v_or_b32_e32 v0, s86, v90
	v_or_b32_e32 v0, s87, v0
	v_ashrrev_i32_e32 v1, 31, v0
	v_lshlrev_b64 v[0:1], 4, v[0:1]
	v_cndmask_b32_e64 v120, 0, 1, s[70:71]
	v_or_b32_e32 v0, v66, v0
	v_readlane_b32 s0, v234, 19
	v_lshl_or_b32 v0, v120, 3, v0
	v_readlane_b32 s1, v234, 20
	s_lshr_b32 s78, s33, 1
	v_mov_b32_e32 v2, v112
	v_lshl_add_u64 v[0:1], v[0:1], 2, s[0:1]
	v_add_co_u32_e32 v4, vcc, 0x100000, v0
	global_load_dword v164, v[0:1], off
	s_nop 0
	v_addc_co_u32_e32 v5, vcc, 0, v1, vcc
	global_load_dword v165, v[4:5], off
	global_load_dword v166, v[0:1], off offset:16
	global_load_dword v167, v[4:5], off offset:16
	s_and_b32 s92, s33, 1
	s_lshl_b32 s0, s92, 8
	s_add_u32 s94, s74, s0
	s_addc_u32 s95, s75, 0
	s_add_i32 s73, s87, s86
	v_add_u32_e32 v0, s73, v85
	v_mov_b64_e32 v[4:5], s[94:95]
	v_and_b32_e32 v6, 0x78, v99
	v_mad_i64_i32 v[4:5], vcc, v0, s72, v[4:5]
	v_lshlrev_b32_e32 v64, 1, v6
	v_lshl_add_u64 v[8:9], v[4:5], 0, v[64:65]
	s_lshl_b32 s98, s72, 5
	s_mov_b32 s99, 0
	global_load_dwordx4 v[132:135], v[8:9], off offset:2560
	global_load_dwordx4 v[136:139], v[8:9], off offset:2048
	v_lshl_add_u64 v[8:9], v[8:9], 0, s[98:99]
	global_load_dwordx4 v[140:143], v[8:9], off offset:2560
	global_load_dwordx4 v[144:147], v[8:9], off offset:2048
	v_lshl_add_u64 v[8:9], v[8:9], 0, s[98:99]
	global_load_dwordx4 v[148:151], v[8:9], off offset:2560
	global_load_dwordx4 v[152:155], v[8:9], off offset:2048
	v_lshl_add_u64 v[8:9], v[8:9], 0, s[98:99]
	global_load_dwordx4 v[156:159], v[8:9], off offset:2560
	global_load_dwordx4 v[160:163], v[8:9], off offset:2048
	s_movk_i32 s84, 0x5ff
	s_waitcnt vmcnt(10)
	ds_write2st64_b32 v112, v164, v165 offset1:16
	s_waitcnt vmcnt(8)
	ds_write2st64_b32 v112, v166, v167 offset0:8 offset1:24
	s_waitcnt vmcnt(7)
	ds_write_b128 v113, v[132:135]
	s_waitcnt vmcnt(6)
	ds_write_b128 v113, v[136:139] offset:34816
	s_waitcnt vmcnt(5)
	ds_write_b128 v113, v[140:143] offset:8704
	s_waitcnt vmcnt(4)
	ds_write_b128 v113, v[144:147] offset:43520
	s_waitcnt vmcnt(3)
	ds_write_b128 v113, v[148:151] offset:17408
	s_waitcnt vmcnt(2)
	ds_write_b128 v113, v[152:155] offset:52224
	s_waitcnt vmcnt(1)
	ds_write_b128 v113, v[156:159] offset:26112
	s_waitcnt vmcnt(0)
	ds_write_b128 v113, v[160:163] offset:60928
	s_waitcnt lgkmcnt(0)
	s_barrier
	ds_read_b128 v[0:3], v91 offset:8192
	ds_read_b128 v[4:7], v115 offset:43008
	ds_read_b128 v[8:11], v115 offset:47360
	ds_read_b128 v[12:15], v115 offset:51712
	ds_read_b128 v[16:19], v115 offset:56064
	ds_read_b128 v[20:23], v115 offset:60416
	ds_read_b128 v[24:27], v115 offset:64768
	ds_read_b128 v[28:31], v116 offset:43008
	ds_read_b128 v[32:35], v117 offset:43008
	s_waitcnt lgkmcnt(7)
	v_mfma_f32_16x16x32_bf16 v[4:7], v[0:3], v[4:7], 0
	s_and_b32 s78, s78, 31
	s_lshl_b32 s78, s78, 7
	s_or_b32 s94, s78, s86
	s_waitcnt lgkmcnt(6)
	v_mfma_f32_16x16x32_bf16 v[8:11], v[0:3], v[8:11], 0
	v_or_b32_e32 v40, s94, v90
	s_lshl_b32 s78, s92, 10
	s_lshl_b32 s0, s96, 4
	s_waitcnt lgkmcnt(5)
	v_mfma_f32_16x16x32_bf16 v[12:15], v[0:3], v[12:15], 0
	v_readfirstlane_b32 s1, v120
	v_mov_b32_e32 v71, v65
	v_readlane_b32 s80, v234, 9
	s_waitcnt lgkmcnt(4)
	v_mfma_f32_16x16x32_bf16 v[16:19], v[0:3], v[16:19], 0
	s_lshl_b32 s1, s1, 3
	v_readlane_b32 s81, v234, 10
	s_movk_i32 s84, 0x3000
	s_waitcnt lgkmcnt(3)
	v_mfma_f32_16x16x32_bf16 v[20:23], v[0:3], v[20:23], 0
	s_lshl_b32 s68, s92, 3
	s_mov_b32 s96, 0
	v_mov_b32_e32 v121, 0
	s_waitcnt lgkmcnt(2)
	v_mfma_f32_16x16x32_bf16 v[24:27], v[0:3], v[24:27], 0
	s_waitcnt lgkmcnt(1)
	v_mfma_f32_16x16x32_bf16 v[28:31], v[0:3], v[28:31], 0
	s_waitcnt lgkmcnt(0)
	v_mfma_f32_16x16x32_bf16 v[0:3], v[0:3], v[32:35], 0
	ds_read_b128 v[32:35], v91 offset:8256
	ds_read_b128 v[36:39], v115 offset:43072
	s_waitcnt lgkmcnt(0)
	v_mfma_f32_16x16x32_bf16 v[4:7], v[32:35], v[36:39], v[4:7]
	ds_read_b128 v[36:39], v115 offset:47424
	s_waitcnt lgkmcnt(0)
	v_mfma_f32_16x16x32_bf16 v[8:11], v[32:35], v[36:39], v[8:11]
	ds_read_b128 v[36:39], v115 offset:51776
	s_waitcnt lgkmcnt(0)
	v_mfma_f32_16x16x32_bf16 v[12:15], v[32:35], v[36:39], v[12:15]
	ds_read_b128 v[36:39], v115 offset:56128
	s_waitcnt lgkmcnt(0)
	v_mfma_f32_16x16x32_bf16 v[16:19], v[32:35], v[36:39], v[16:19]
	ds_read_b128 v[36:39], v115 offset:60480
	s_waitcnt lgkmcnt(0)
	v_mfma_f32_16x16x32_bf16 v[20:23], v[32:35], v[36:39], v[20:23]
	ds_read_b128 v[36:39], v115 offset:64832
	s_waitcnt lgkmcnt(0)
	v_mfma_f32_16x16x32_bf16 v[24:27], v[32:35], v[36:39], v[24:27]
	ds_read_b128 v[36:39], v116 offset:43072
	s_waitcnt lgkmcnt(0)
	v_mfma_f32_16x16x32_bf16 v[28:31], v[32:35], v[36:39], v[28:31]
	ds_read_b128 v[36:39], v117 offset:43072
	s_waitcnt lgkmcnt(0)
	v_mfma_f32_16x16x32_bf16 v[0:3], v[32:35], v[36:39], v[0:3]
	ds_read_b128 v[32:35], v91 offset:8320
	ds_read_b128 v[36:39], v115 offset:43136
	s_waitcnt lgkmcnt(0)
	v_mfma_f32_16x16x32_bf16 v[4:7], v[32:35], v[36:39], v[4:7]
	ds_read_b128 v[36:39], v115 offset:47488
	s_waitcnt lgkmcnt(0)
	v_mfma_f32_16x16x32_bf16 v[8:11], v[32:35], v[36:39], v[8:11]
	ds_read_b128 v[36:39], v115 offset:51840
	s_waitcnt lgkmcnt(0)
	v_mfma_f32_16x16x32_bf16 v[12:15], v[32:35], v[36:39], v[12:15]
	ds_read_b128 v[36:39], v115 offset:56192
	s_waitcnt lgkmcnt(0)
	v_mfma_f32_16x16x32_bf16 v[16:19], v[32:35], v[36:39], v[16:19]
	ds_read_b128 v[36:39], v115 offset:60544
	s_waitcnt lgkmcnt(0)
	v_mfma_f32_16x16x32_bf16 v[20:23], v[32:35], v[36:39], v[20:23]
	ds_read_b128 v[36:39], v115 offset:64896
	s_waitcnt lgkmcnt(0)
	v_mfma_f32_16x16x32_bf16 v[24:27], v[32:35], v[36:39], v[24:27]
	ds_read_b128 v[36:39], v116 offset:43136
	s_waitcnt lgkmcnt(0)
	v_mfma_f32_16x16x32_bf16 v[28:31], v[32:35], v[36:39], v[28:31]
	ds_read_b128 v[36:39], v117 offset:43136
	s_waitcnt lgkmcnt(0)
	v_mfma_f32_16x16x32_bf16 v[32:35], v[32:35], v[36:39], v[0:3]
	ds_read_b128 v[36:39], v91 offset:8384
	s_nop 1
	ds_read_b128 v[0:3], v115 offset:43200
	s_waitcnt lgkmcnt(0)
	v_mfma_f32_16x16x32_bf16 v[0:3], v[36:39], v[0:3], v[4:7]
	s_nop 2
	ds_read_b128 v[4:7], v115 offset:47552
	s_waitcnt lgkmcnt(0)
	v_mfma_f32_16x16x32_bf16 v[4:7], v[36:39], v[4:7], v[8:11]
	s_nop 2
	ds_read_b128 v[8:11], v115 offset:51904
	s_waitcnt lgkmcnt(0)
	v_mfma_f32_16x16x32_bf16 v[8:11], v[36:39], v[8:11], v[12:15]
	s_nop 2
	ds_read_b128 v[12:15], v115 offset:56256
	s_waitcnt lgkmcnt(0)
	v_mfma_f32_16x16x32_bf16 v[12:15], v[36:39], v[12:15], v[16:19]
	s_nop 2
	ds_read_b128 v[16:19], v115 offset:60608
	s_waitcnt lgkmcnt(0)
	v_mfma_f32_16x16x32_bf16 v[16:19], v[36:39], v[16:19], v[20:23]
	s_nop 2
	ds_read_b128 v[20:23], v115 offset:64960
	s_waitcnt lgkmcnt(0)
	v_mfma_f32_16x16x32_bf16 v[20:23], v[36:39], v[20:23], v[24:27]
	s_nop 2
	ds_read_b128 v[24:27], v116 offset:43200
	s_waitcnt lgkmcnt(0)
	v_mfma_f32_16x16x32_bf16 v[24:27], v[36:39], v[24:27], v[28:31]
	s_nop 2
	ds_read_b128 v[28:31], v117 offset:43200
	s_waitcnt lgkmcnt(0)
	v_mfma_f32_16x16x32_bf16 v[28:31], v[36:39], v[28:31], v[32:35]
	s_nop 2
	v_mov_b64_e32 v[32:33], s[74:75]
	v_mad_i64_i32 v[34:35], vcc, v40, s72, v[32:33]
	v_lshl_add_u64 v[34:35], v[34:35], 0, s[78:79]
	s_lshl_b32 s78, s97, 9
	v_lshl_add_u64 v[72:73], v[34:35], 0, v[70:71]
	v_add_u32_e32 v34, s94, v92
	s_or_b32 s0, s78, s0
	v_mad_i64_i32 v[74:75], s[94:95], v34, s72, v[32:33]
	v_mov_b64_e32 v[32:33], s[80:81]
	s_or_b32 s0, s0, s1
	v_ashrrev_i32_e32 v35, 31, v34
	v_mad_i64_i32 v[76:77], s[94:95], v34, s84, v[32:33]
	v_readlane_b32 s84, v234, 7
	s_ashr_i32 s1, s0, 31
	v_lshlrev_b64 v[32:33], 12, v[34:35]
	v_readlane_b32 s85, v234, 8
	s_lshl_b64 s[0:1], s[0:1], 14
	v_lshl_or_b32 v71, s92, 9, v93
	v_lshl_add_u64 v[78:79], s[84:85], 0, v[32:33]
	v_lshl_add_u64 v[80:81], v[68:69], 0, s[0:1]
	s_barrier
	s_mov_b32 s98, 0
	s_lshl_b32 s100, s98, 7
	s_mov_b32 s101, 0
	v_lshl_add_u64 v[254:255], v[72:73], 0, s[100:101]
	global_load_dwordx4 v[132:135], v[254:255], off offset:16
	global_load_dwordx4 v[136:139], v[254:255], off
	s_sub_i32 s100, s98, s96
	s_lshl_b32 s100, s100, 14
	v_lshl_add_u64 v[254:255], v[80:81], 0, s[100:101]
	global_load_dwordx4 v[140:143], v[254:255], off
	s_add_i32 s100, s100, 0x2000
	v_lshl_add_u64 v[254:255], v[80:81], 0, s[100:101]
	global_load_dwordx4 v[144:147], v[254:255], off
	s_add_i32 s98, s98, s68
	s_lshl_b32 s98, s98, 2
	v_readlane_b32 s100, v235, 23
	v_readlane_b32 s101, v235, 24
	s_nop 3
	s_add_u32 s100, s100, s98
	s_addc_u32 s101, s101, 0
	global_load_dword v148, v65, s[100:101]
	global_load_dword v150, v65, s[100:101]
	global_load_dword v151, v65, s[100:101]
	global_load_dword v152, v65, s[100:101]
	global_load_dword v153, v65, s[100:101]
